# lat-A loop: second V^T pair of the second key sub-block read together with the first pair (no serialized read-wait steps, no v_mov shuffles)
# baseline (speedup 1.0000x reference)
.LBB0_225:
	v_sub_f32_e32 v4, v96, v1
	v_exp_f32_e32 v9, v4
	v_sub_f32_e32 v5, v97, v1
	v_exp_f32_e32 v10, v5
	v_sub_f32_e32 v5, v98, v1
	v_exp_f32_e32 v11, v5
	v_sub_f32_e32 v5, v99, v1
	v_exp_f32_e32 v13, v5
	v_sub_f32_e32 v5, v100, v1
	v_add_f32_e32 v4, 0, v9
	v_exp_f32_e32 v14, v5
	v_sub_f32_e32 v5, v101, v1
	v_add_f32_e32 v4, v10, v4
	v_exp_f32_e32 v15, v5
	v_sub_f32_e32 v5, v102, v1
	v_add_f32_e32 v4, v11, v4
	v_exp_f32_e32 v96, v5
	v_sub_f32_e32 v5, v103, v1
	v_add_f32_e32 v4, v13, v4
	v_exp_f32_e32 v97, v5
	v_sub_f32_e32 v5, v104, v1
	v_add_f32_e32 v4, v14, v4
	v_exp_f32_e32 v5, v5
	v_sub_f32_e32 v6, v105, v1
	v_add_f32_e32 v4, v15, v4
	v_exp_f32_e32 v6, v6
	v_sub_f32_e32 v7, v106, v1
	v_add_f32_e32 v4, v96, v4
	v_exp_f32_e32 v7, v7
	v_sub_f32_e32 v12, v107, v1
	v_add_f32_e32 v4, v97, v4
	v_exp_f32_e32 v12, v12
	v_sub_f32_e32 v98, v108, v1
	v_add_f32_e32 v4, v5, v4
	v_exp_f32_e32 v98, v98
	v_sub_f32_e32 v99, v109, v1
	v_add_f32_e32 v4, v6, v4
	v_exp_f32_e32 v99, v99
	v_sub_f32_e32 v100, v110, v1
	v_add_f32_e32 v4, v7, v4
	v_exp_f32_e32 v100, v100
	v_sub_f32_e32 v101, v111, v1
	v_add_f32_e32 v4, v12, v4
	v_exp_f32_e32 v101, v101
	v_add_f32_e32 v4, v98, v4
	v_add_f32_e32 v4, v99, v4
	v_add_f32_e32 v4, v100, v4
	v_add_f32_e32 v4, v101, v4
	v_add_f32_e32 v3, v3, v4
	v_cvt_pk_bf16_f32 v4, v5, v6
	v_cvt_pk_bf16_f32 v5, v7, v12
	v_cvt_pk_bf16_f32 v12, v9, v10
	v_sub_f32_e32 v9, v80, v159
	v_cvt_pk_bf16_f32 v13, v11, v13
	v_exp_f32_e32 v9, v9
	v_sub_f32_e32 v11, v81, v159
	v_exp_f32_e32 v11, v11
	v_sub_f32_e32 v80, v82, v159
	v_exp_f32_e32 v81, v80
	v_sub_f32_e32 v80, v83, v159
	v_exp_f32_e32 v82, v80
	v_sub_f32_e32 v80, v84, v159
	v_add_f32_e32 v10, 0, v9
	v_exp_f32_e32 v83, v80
	v_sub_f32_e32 v80, v85, v159
	v_add_f32_e32 v10, v11, v10
	v_exp_f32_e32 v84, v80
	v_sub_f32_e32 v80, v86, v159
	v_add_f32_e32 v10, v81, v10
	v_exp_f32_e32 v85, v80
	v_sub_f32_e32 v80, v87, v159
	v_add_f32_e32 v10, v82, v10
	v_exp_f32_e32 v86, v80
	v_sub_f32_e32 v80, v88, v159
	v_add_f32_e32 v10, v83, v10
	v_exp_f32_e32 v87, v80
	v_sub_f32_e32 v80, v89, v159
	v_add_f32_e32 v10, v84, v10
	v_exp_f32_e32 v88, v80
	v_sub_f32_e32 v80, v90, v159
	v_add_f32_e32 v10, v85, v10
	v_exp_f32_e32 v89, v80
	v_sub_f32_e32 v80, v91, v159
	v_add_f32_e32 v10, v86, v10
	v_exp_f32_e32 v90, v80
	v_sub_f32_e32 v80, v92, v159
	v_add_f32_e32 v10, v87, v10
	v_exp_f32_e32 v91, v80
	v_sub_f32_e32 v80, v93, v159
	v_add_f32_e32 v10, v88, v10
	v_exp_f32_e32 v92, v80
	v_sub_f32_e32 v80, v94, v159
	v_add_f32_e32 v10, v89, v10
	v_exp_f32_e32 v93, v80
	v_sub_f32_e32 v80, v95, v159
	v_add_f32_e32 v10, v90, v10
	v_exp_f32_e32 v94, v80
	v_add_f32_e32 v10, v91, v10
	v_add_f32_e32 v10, v92, v10
	v_add_f32_e32 v10, v93, v10
	v_add_f32_e32 v10, v94, v10
	v_add_f32_e32 v162, v8, v10
	v_cvt_pk_bf16_f32 v81, v81, v82
	v_cvt_pk_bf16_f32 v82, v83, v84
	v_cvt_pk_bf16_f32 v8, v87, v88
	v_lshl_add_u32 v84, v158, 1, v204
	v_lshl_add_u32 v88, v157, 1, v204
	v_cvt_pk_bf16_f32 v80, v9, v11
	v_cvt_pk_bf16_f32 v83, v85, v86
	v_cvt_pk_bf16_f32 v9, v89, v90
	v_cvt_pk_bf16_f32 v10, v91, v92
	ds_read_b64 v[222:223], v84 offset:8192
	ds_read_b64 v[226:227], v84 offset:12288
	ds_read_b64 v[224:225], v88 offset:8192
	ds_read_b64 v[228:229], v88 offset:12288
	v_lshl_add_u32 v246, v156, 1, v204
	v_lshl_add_u32 v247, v155, 1, v204
	ds_read_b64 v[238:239], v246 offset:8192
	ds_read_b64 v[242:243], v246 offset:12288
	ds_read_b64 v[240:241], v247 offset:8192
	ds_read_b64 v[244:245], v247 offset:12288
	v_cvt_pk_bf16_f32 v11, v93, v94
	v_cvt_pk_bf16_f32 v14, v14, v15
	v_cvt_pk_bf16_f32 v15, v96, v97
	s_waitcnt lgkmcnt(0)
	v_mfma_f32_32x32x16_bf16 v[64:79], v[222:225], v[12:15], v[64:79]
	v_cvt_pk_bf16_f32 v6, v98, v99
	v_cvt_pk_bf16_f32 v7, v100, v101
	s_add_i32 s40, s40, 1
	s_add_i32 s2, s41, 1
	s_cmp_lg_u32 s41, 2
	s_cselect_b32 s41, s2, 0
	s_mov_b64 s[2:3], 0x2000
	v_mfma_f32_32x32x16_bf16 v[32:47], v[222:225], v[80:83], v[32:47]
	v_lshl_add_u64 v[150:151], v[150:151], 0, s[22:23]
	v_lshl_add_u64 v[152:153], v[152:153], 0, s[2:3]
	s_cmp_lg_u32 s40, 3
	v_mfma_f32_32x32x16_bf16 v[48:63], v[226:229], v[12:15], v[48:63]
	v_mfma_f32_32x32x16_bf16 v[16:31], v[226:229], v[80:83], v[16:31]
	v_mfma_f32_32x32x16_bf16 v[64:79], v[238:241], v[4:7], v[64:79]
	v_mfma_f32_32x32x16_bf16 v[32:47], v[238:241], v[8:11], v[32:47]
	v_mfma_f32_32x32x16_bf16 v[48:63], v[242:245], v[4:7], v[48:63]
	v_mfma_f32_32x32x16_bf16 v[16:31], v[242:245], v[8:11], v[16:31]
	s_cbranch_scc0 .LBB0_236
